# v16 + MLA loop-edge edits: 6-instruction uniform-branch ballot after the row max trimmed to v_cmp/s_cmp/s_cbranch, s_nop 7 after QK reduced to s_nop 0 (V prefetch reads supply the MFMA distance)
# speedup vs baseline: 1.0013x; 1.0010x over previous
.LBB0_547:
	s_nop 0
	v_max_f32_e32 v84, v101, v101
	v_max_f32_e32 v85, v100, v100
	v_max_f32_e32 v84, v85, v84
	v_max3_f32 v85, v102, v103, v117
	v_max3_f32 v84, v84, v116, v118
	v_max3_f32 v84, v84, v119, v104
	v_max3_f32 v85, v85, v106, v107
	v_max3_f32 v84, v84, v105, v120
	v_max3_f32 v85, v85, v122, v123
	v_max3_f32 v84, v84, v121, v108
	v_max3_f32 v85, v85, v110, v111
	v_max3_f32 v84, v84, v109, v124
	v_max3_f32 v85, v85, v126, v127
	v_max3_f32 v84, v84, v125, v112
	v_max3_f32 v85, v85, v114, v115
	v_max3_f32 v84, v84, v113, v128
	v_max3_f32 v85, v85, v130, v131
	v_max3_f32 v84, v84, v129, v85
	v_mov_b32_e32 v85, v84
	s_nop 1
	v_permlane32_swap_b32_e32 v84, v85
	s_cmp_eq_u32 s53, 0
	v_max_f32_e32 v85, v85, v85
	v_max_f32_e32 v84, v84, v84
	s_cselect_b64 s[40:41], -1, 0
	s_cmp_lg_u32 s53, 0
	v_max_f32_e32 v84, v84, v85
	s_cbranch_scc0 .LBB0_566
	s_mov_b32 s3, 0x4138aa3b
	v_cmp_lt_f32_e32 vcc, s3, v84
	v_mov_b32_e32 v235, 1.0
	s_cmp_lg_u64 vcc, 0
	s_cbranch_scc0 .LBB0_553
	s_branch .Lmla_resc1

.Lmla_resc1:
	v_max_f32_e32 v68, v84, v84
	v_max_f32_e32 v68, 0, v68
	v_cndmask_b32_e64 v68, v68, v84, s[40:41]
	v_pk_add_f32 v[100:101], v[100:101], v[68:69] op_sel_hi:[1,0] neg_lo:[0,1] neg_hi:[0,1]
	v_pk_add_f32 v[116:117], v[116:117], v[68:69] op_sel_hi:[1,0] neg_lo:[0,1] neg_hi:[0,1]
	v_pk_add_f32 v[102:103], v[102:103], v[68:69] op_sel_hi:[1,0] neg_lo:[0,1] neg_hi:[0,1]
	v_pk_add_f32 v[118:119], v[118:119], v[68:69] op_sel_hi:[1,0] neg_lo:[0,1] neg_hi:[0,1]
	v_pk_add_f32 v[104:105], v[104:105], v[68:69] op_sel_hi:[1,0] neg_lo:[0,1] neg_hi:[0,1]
	v_pk_add_f32 v[120:121], v[120:121], v[68:69] op_sel_hi:[1,0] neg_lo:[0,1] neg_hi:[0,1]
	v_pk_add_f32 v[106:107], v[106:107], v[68:69] op_sel_hi:[1,0] neg_lo:[0,1] neg_hi:[0,1]
	v_pk_add_f32 v[122:123], v[122:123], v[68:69] op_sel_hi:[1,0] neg_lo:[0,1] neg_hi:[0,1]
	v_pk_add_f32 v[108:109], v[108:109], v[68:69] op_sel_hi:[1,0] neg_lo:[0,1] neg_hi:[0,1]
	v_pk_add_f32 v[124:125], v[124:125], v[68:69] op_sel_hi:[1,0] neg_lo:[0,1] neg_hi:[0,1]
	v_pk_add_f32 v[110:111], v[110:111], v[68:69] op_sel_hi:[1,0] neg_lo:[0,1] neg_hi:[0,1]
	v_pk_add_f32 v[126:127], v[126:127], v[68:69] op_sel_hi:[1,0] neg_lo:[0,1] neg_hi:[0,1]
	v_pk_add_f32 v[112:113], v[112:113], v[68:69] op_sel_hi:[1,0] neg_lo:[0,1] neg_hi:[0,1]
	v_pk_add_f32 v[128:129], v[128:129], v[68:69] op_sel_hi:[1,0] neg_lo:[0,1] neg_hi:[0,1]
	v_exp_f32_e64 v69, -v68
	v_add_f32_e32 v234, v234, v68
	v_xor_b32_e32 v84, 0x80000000, v234
	v_mov_b32_e32 v85, v84
	v_pk_add_f32 v[114:115], v[114:115], v[68:69] op_sel_hi:[1,0] neg_lo:[0,1] neg_hi:[0,1]
	v_pk_add_f32 v[130:131], v[130:131], v[68:69] op_sel_hi:[1,0] neg_lo:[0,1] neg_hi:[0,1]
	v_cndmask_b32_e64 v235, v69, 1.0, s[40:41]
	v_mov_b32_e32 v86, v84
	v_mov_b32_e32 v87, v84
	v_mov_b32_e32 v88, v84
	v_mov_b32_e32 v89, v84
	v_mov_b32_e32 v90, v84
	v_mov_b32_e32 v91, v84
	v_mov_b32_e32 v92, v84
	v_mov_b32_e32 v93, v84
	v_mov_b32_e32 v94, v84
	v_mov_b32_e32 v95, v84
	v_mov_b32_e32 v96, v84
	v_mov_b32_e32 v97, v84
	v_mov_b32_e32 v98, v84
	v_mov_b32_e32 v99, v84
	v_mov_b32_e32 v68, v84
	v_mov_b32_e32 v69, v84
	v_mov_b32_e32 v70, v84
	v_mov_b32_e32 v71, v84
	v_mov_b32_e32 v72, v84
	v_mov_b32_e32 v73, v84
	v_mov_b32_e32 v74, v84
	v_mov_b32_e32 v75, v84
	v_mov_b32_e32 v76, v84
	v_mov_b32_e32 v77, v84
	v_mov_b32_e32 v78, v84
	v_mov_b32_e32 v79, v84
	v_mov_b32_e32 v80, v84
	v_mov_b32_e32 v81, v84
	v_mov_b32_e32 v82, v84
	v_mov_b32_e32 v83, v84
	s_branch .LBB0_554

.LBB0_562:
	s_nop 0
	v_max_f32_e32 v116, v101, v101
	v_max_f32_e32 v117, v100, v100
	v_max_f32_e32 v116, v117, v116
	v_max3_f32 v117, v102, v103, v85
	v_max3_f32 v116, v116, v84, v86
	v_max3_f32 v116, v116, v87, v104
	v_max3_f32 v117, v117, v106, v107
	v_max3_f32 v116, v116, v105, v88
	v_max3_f32 v117, v117, v90, v91
	v_max3_f32 v116, v116, v89, v108
	v_max3_f32 v117, v117, v110, v111
	v_max3_f32 v116, v116, v109, v92
	v_max3_f32 v117, v117, v94, v95
	v_max3_f32 v116, v116, v93, v112
	v_max3_f32 v117, v117, v114, v115
	v_max3_f32 v116, v116, v113, v96
	v_max3_f32 v117, v117, v98, v99
	v_max3_f32 v116, v116, v97, v117
	v_mov_b32_e32 v117, v116
	s_nop 1
	v_permlane32_swap_b32_e32 v116, v117
	v_max_f32_e32 v117, v117, v117
	v_max_f32_e32 v116, v116, v116
	v_max_f32_e32 v117, v116, v117
	s_mov_b32 s3, 0x4138aa3b
	v_cmp_lt_f32_e32 vcc, s3, v117
	v_mov_b32_e32 v116, 1.0
	s_cbranch_vccnz .LBB0_567
